# resid epilogue head: first two next-norm/norm-weight vector pairs loaded early into dead registers, two serialized waits removed
# speedup vs baseline: 1.0103x; 1.0002x over previous
.LBB0_1021:
	s_add_i32 vcc_hi, s46, 2
	s_add_u32 s84, s44, 0x80
	s_addc_u32 s47, s45, 0
	s_add_i32 s29, 0, 0x10000
	v_add_u32_e32 v96, s29, v225
	ds_read_b128 v[56:59], v96
	ds_read_b128 v[68:71], v96 offset:1024
	s_cmp_eq_u32 s90, s46
	s_cselect_b32 s46, s80, s84
	s_cselect_b32 s47, s81, s47
	s_cselect_b32 s85, s83, vcc_lo
	s_cselect_b32 s84, s82, s87
	s_add_i32 m0, s2, 0xc000
	ds_read_b128 v[102:105], v227
	ds_read_b128 v[112:115], v227 offset:1024
	ds_read_b128 v[124:127], v227 offset:2048
	ds_read_b128 v[192:195], v227 offset:3072
	ds_read_b128 v[196:199], v227 offset:4096
	ds_read_b128 v[200:203], v227 offset:5120
	global_load_lds_dwordx4 v188, s[44:45]
	s_add_i32 m0, s2, 0xe000
	s_mov_b64 exec, s[98:99]
	global_load_lds_dwordx4 v190, s[44:45]
	s_mov_b64 exec, -1
	s_waitcnt lgkmcnt(6)
	s_setprio 1
	s_barrier
	s_waitcnt lgkmcnt(0)
	v_mfma_f32_16x16x32_bf16 v[172:175], v[56:59], v[102:105], v[172:175]
	v_mfma_f32_16x16x32_bf16 v[168:171], v[80:83], v[102:105], v[168:171]
	v_mfma_f32_16x16x32_bf16 v[156:159], v[56:59], v[124:127], v[156:159]
	v_mfma_f32_16x16x32_bf16 v[152:155], v[80:83], v[124:127], v[152:155]
	v_mfma_f32_16x16x32_bf16 v[132:135], v[56:59], v[196:199], v[132:135]
	v_mfma_f32_16x16x32_bf16 v[128:131], v[80:83], v[196:199], v[128:131]
	v_mfma_f32_16x16x32_bf16 v[172:175], v[68:71], v[112:115], v[172:175]
	v_mfma_f32_16x16x32_bf16 v[168:171], v[98:101], v[112:115], v[168:171]
	v_mfma_f32_16x16x32_bf16 v[156:159], v[68:71], v[192:195], v[156:159]
	v_mfma_f32_16x16x32_bf16 v[152:155], v[98:101], v[192:195], v[152:155]
	v_mfma_f32_16x16x32_bf16 v[132:135], v[68:71], v[200:203], v[132:135]
	v_mfma_f32_16x16x32_bf16 v[128:131], v[98:101], v[200:203], v[128:131]
	s_barrier
	s_setprio 0
	s_add_i32 s96, 0, 0x14000
	s_add_i32 s29, s29, s18
	v_add_u32_e32 v96, s96, v225
	v_lshl_add_u64 v[106:107], s[84:85], 0, v[182:183]
	s_mov_b32 m0, s29
	ds_read_b128 v[228:231], v96
	ds_read_b128 v[232:235], v96 offset:1024
	ds_read_b128 v[236:239], v96 offset:2048
	ds_read_b128 v[240:243], v96 offset:3072
	global_load_lds_dwordx4 v182, s[84:85]
	v_lshl_add_u64 v[248:249], s[84:85], 0, v[186:187]
	s_add_i32 m0, s29, 0x2000
	s_nop 0
	global_load_lds_dwordx4 v186, s[84:85]
	s_setprio 1
	s_barrier
	s_waitcnt lgkmcnt(0)
	v_mfma_f32_16x16x32_bf16 v[164:167], v[228:231], v[102:105], v[164:167]
	v_mfma_f32_16x16x32_bf16 v[102:105], v[236:239], v[102:105], v[160:163]
	v_mfma_f32_16x16x32_bf16 v[120:123], v[228:231], v[196:199], v[120:123]
	s_mov_b32 m0, s2
	v_mfma_f32_16x16x32_bf16 v[116:119], v[236:239], v[196:199], v[116:119]
	v_lshl_add_u64 v[250:251], s[46:47], 0, v[176:177]
	v_mfma_f32_16x16x32_bf16 v[164:167], v[232:235], v[112:115], v[164:167]
	v_mfma_f32_16x16x32_bf16 v[102:105], v[240:243], v[112:115], v[102:105]
	v_mfma_f32_16x16x32_bf16 v[112:115], v[228:231], v[124:127], v[148:151]
	v_mfma_f32_16x16x32_bf16 v[124:127], v[236:239], v[124:127], v[144:147]
	v_mfma_f32_16x16x32_bf16 v[120:123], v[232:235], v[200:203], v[120:123]
	v_mfma_f32_16x16x32_bf16 v[116:119], v[240:243], v[200:203], v[116:119]
	v_mfma_f32_16x16x32_bf16 v[112:115], v[232:235], v[192:195], v[112:115]
	v_mfma_f32_16x16x32_bf16 v[124:127], v[240:243], v[192:195], v[124:127]
	s_barrier
	s_setprio 0
	ds_read_b128 v[144:147], v227 offset:16384
	ds_read_b128 v[148:151], v227 offset:17408
	ds_read_b128 v[160:163], v227 offset:18432
	ds_read_b128 v[192:195], v227 offset:19456
	ds_read_b128 v[196:199], v227 offset:20480
	ds_read_b128 v[200:203], v227 offset:21504
	global_load_lds_dwordx4 v176, s[46:47]
	v_lshl_add_u64 v[252:253], s[46:47], 0, v[184:185]
	s_mov_b32 m0, s3
	s_mov_b64 exec, s[98:99]
	global_load_lds_dwordx4 v184, s[46:47]
	s_mov_b64 exec, -1
	s_waitcnt vmcnt(10)
	s_setprio 1
	s_barrier
	s_waitcnt lgkmcnt(0)
	v_mfma_f32_16x16x32_bf16 v[88:91], v[56:59], v[144:147], v[88:91]
	v_mfma_f32_16x16x32_bf16 v[84:87], v[80:83], v[144:147], v[84:87]
	v_mfma_f32_16x16x32_bf16 v[52:55], v[56:59], v[160:163], v[52:55]
	v_mfma_f32_16x16x32_bf16 v[48:51], v[80:83], v[160:163], v[48:51]
	v_mfma_f32_16x16x32_bf16 v[28:31], v[56:59], v[196:199], v[28:31]
	v_mfma_f32_16x16x32_bf16 v[24:27], v[80:83], v[196:199], v[24:27]
	v_mfma_f32_16x16x32_bf16 v[88:91], v[68:71], v[148:151], v[88:91]
	v_mfma_f32_16x16x32_bf16 v[84:87], v[98:101], v[148:151], v[84:87]
	v_mfma_f32_16x16x32_bf16 v[52:55], v[68:71], v[192:195], v[52:55]
	v_mfma_f32_16x16x32_bf16 v[48:51], v[98:101], v[192:195], v[48:51]
	v_mfma_f32_16x16x32_bf16 v[28:31], v[68:71], v[200:203], v[28:31]
	v_mfma_f32_16x16x32_bf16 v[24:27], v[98:101], v[200:203], v[24:27]
	s_barrier
	s_setprio 0
	v_add_u32_e32 v96, 0x18000, v225
	ds_read_b128 v[80:83], v96 offset:2048
	ds_read_b128 v[98:101], v96 offset:3072
	s_add_u32 s84, s84, s57
	s_addc_u32 s85, s85, 0
	s_add_i32 s29, s96, s18
	v_lshl_add_u64 v[218:219], s[84:85], 0, v[182:183]
	s_mov_b32 m0, s29
	v_lshl_add_u64 v[220:221], s[84:85], 0, v[186:187]
	global_load_lds_dwordx4 v182, s[84:85]
	s_add_i32 m0, s29, 0x2000
	s_nop 0
	global_load_lds_dwordx4 v186, s[84:85]
	s_waitcnt vmcnt(6)
	s_setprio 1
	s_barrier
	v_mfma_f32_16x16x32_bf16 v[44:47], v[228:231], v[160:163], v[44:47]
	v_mfma_f32_16x16x32_bf16 v[40:43], v[236:239], v[160:163], v[40:43]
	v_mfma_f32_16x16x32_bf16 v[20:23], v[228:231], v[196:199], v[20:23]
	s_add_i32 s29, 0, 0x18000
	v_mfma_f32_16x16x32_bf16 v[16:19], v[236:239], v[196:199], v[16:19]
	v_add_u32_e32 v96, s29, v225
	v_mfma_f32_16x16x32_bf16 v[56:59], v[228:231], v[144:147], v[76:79]
	v_mfma_f32_16x16x32_bf16 v[68:71], v[236:239], v[144:147], v[72:75]
	v_mfma_f32_16x16x32_bf16 v[44:47], v[232:235], v[192:195], v[44:47]
	v_mfma_f32_16x16x32_bf16 v[40:43], v[240:243], v[192:195], v[40:43]
	v_mfma_f32_16x16x32_bf16 v[20:23], v[232:235], v[200:203], v[20:23]
	v_mfma_f32_16x16x32_bf16 v[16:19], v[240:243], v[200:203], v[16:19]
	v_mfma_f32_16x16x32_bf16 v[56:59], v[232:235], v[148:151], v[56:59]
	v_mfma_f32_16x16x32_bf16 v[68:71], v[240:243], v[148:151], v[68:71]
	s_barrier
	s_setprio 0
	ds_read_b128 v[72:75], v96
	ds_read_b128 v[76:79], v96 offset:1024
	s_add_u32 s46, s46, s64
	s_addc_u32 s47, s47, 0
	s_mov_b32 m0, s4
	ds_read_b128 v[144:147], v227 offset:32768
	ds_read_b128 v[148:151], v227 offset:33792
	ds_read_b128 v[192:195], v227 offset:34816
	ds_read_b128 v[196:199], v227 offset:35840
	ds_read_b128 v[200:203], v227 offset:36864
	ds_read_b128 v[228:231], v227 offset:37888
	global_load_lds_dwordx4 v176, s[46:47]
	s_mov_b32 m0, s5
	s_mov_b64 exec, s[98:99]
	global_load_lds_dwordx4 v184, s[46:47]
	s_mov_b64 exec, -1
	s_waitcnt lgkmcnt(6)
	s_setprio 1
	s_barrier
	s_waitcnt lgkmcnt(0)
	v_mfma_f32_16x16x32_bf16 v[160:163], v[72:75], v[144:147], v[172:175]
	v_mfma_f32_16x16x32_bf16 v[172:175], v[76:79], v[148:151], v[160:163]
	v_mfma_f32_16x16x32_bf16 v[160:163], v[80:83], v[144:147], v[168:171]
	v_mfma_f32_16x16x32_bf16 v[156:159], v[72:75], v[192:195], v[156:159]
	v_mfma_f32_16x16x32_bf16 v[152:155], v[80:83], v[192:195], v[152:155]
	v_mfma_f32_16x16x32_bf16 v[132:135], v[72:75], v[200:203], v[132:135]
	v_mfma_f32_16x16x32_bf16 v[128:131], v[80:83], v[200:203], v[128:131]
	v_mfma_f32_16x16x32_bf16 v[168:171], v[98:101], v[148:151], v[160:163]
	v_mfma_f32_16x16x32_bf16 v[156:159], v[76:79], v[196:199], v[156:159]
	v_mfma_f32_16x16x32_bf16 v[152:155], v[98:101], v[196:199], v[152:155]
	v_mfma_f32_16x16x32_bf16 v[132:135], v[76:79], v[228:231], v[132:135]
	v_mfma_f32_16x16x32_bf16 v[128:131], v[98:101], v[228:231], v[128:131]
	s_barrier
	s_setprio 0
	s_add_i32 s46, 0, 0x1c000
	s_add_i32 s29, s29, s18
	v_add_u32_e32 v96, s46, v225
	v_lshl_add_u64 v[106:107], v[106:107], 0, s[6:7]
	s_mov_b32 m0, s29
	ds_read_b128 v[232:235], v96
	ds_read_b128 v[236:239], v96 offset:1024
	ds_read_b128 v[240:243], v96 offset:2048
	ds_read_b128 v[244:247], v96 offset:3072
	global_load_lds_dwordx4 v[106:107], off
	v_lshl_add_u64 v[106:107], v[248:249], 0, s[6:7]
	s_add_i32 m0, s29, 0x2000
	s_nop 0
	global_load_lds_dwordx4 v[106:107], off
	s_setprio 1
	s_barrier
	s_waitcnt lgkmcnt(0)
	v_mfma_f32_16x16x32_bf16 v[160:163], v[232:235], v[144:147], v[164:167]
	v_mfma_f32_16x16x32_bf16 v[102:105], v[240:243], v[144:147], v[102:105]
	v_mfma_f32_16x16x32_bf16 v[164:167], v[236:239], v[148:151], v[160:163]
	s_mov_b32 m0, s88
	v_mfma_f32_16x16x32_bf16 v[160:163], v[244:247], v[148:151], v[102:105]
	v_lshl_add_u64 v[106:107], v[250:251], 0, s[6:7]
	v_mfma_f32_16x16x32_bf16 v[102:105], v[232:235], v[192:195], v[112:115]
	v_mfma_f32_16x16x32_bf16 v[148:151], v[236:239], v[196:199], v[102:105]
	v_mfma_f32_16x16x32_bf16 v[102:105], v[240:243], v[192:195], v[124:127]
	v_mfma_f32_16x16x32_bf16 v[144:147], v[244:247], v[196:199], v[102:105]
	v_mfma_f32_16x16x32_bf16 v[102:105], v[232:235], v[200:203], v[120:123]
	v_mfma_f32_16x16x32_bf16 v[120:123], v[236:239], v[228:231], v[102:105]
	v_mfma_f32_16x16x32_bf16 v[102:105], v[240:243], v[200:203], v[116:119]
	v_mfma_f32_16x16x32_bf16 v[116:119], v[244:247], v[228:231], v[102:105]
	s_barrier
	s_setprio 0
	s_nop 2
	ds_read_b128 v[102:105], v227 offset:49152
	ds_read_b128 v[112:115], v227 offset:50176
	ds_read_b128 v[124:127], v227 offset:51200
	ds_read_b128 v[192:195], v227 offset:52224
	ds_read_b128 v[196:199], v227 offset:53248
	ds_read_b128 v[200:203], v227 offset:54272
	global_load_lds_dwordx4 v[106:107], off
	v_lshl_add_u64 v[106:107], v[252:253], 0, s[6:7]
	s_mov_b32 m0, s89
	s_mov_b64 exec, s[98:99]
	global_load_lds_dwordx4 v[106:107], off
	s_mov_b64 exec, -1
	s_waitcnt vmcnt(10)
	s_setprio 1
	s_barrier
	s_waitcnt lgkmcnt(0)
	v_mfma_f32_16x16x32_bf16 v[88:91], v[72:75], v[102:105], v[88:91]
	v_mfma_f32_16x16x32_bf16 v[84:87], v[80:83], v[102:105], v[84:87]
	v_mfma_f32_16x16x32_bf16 v[52:55], v[72:75], v[124:127], v[52:55]
	v_mfma_f32_16x16x32_bf16 v[48:51], v[80:83], v[124:127], v[48:51]
	v_mfma_f32_16x16x32_bf16 v[28:31], v[72:75], v[196:199], v[28:31]
	v_mfma_f32_16x16x32_bf16 v[24:27], v[80:83], v[196:199], v[24:27]
	v_mfma_f32_16x16x32_bf16 v[88:91], v[76:79], v[112:115], v[88:91]
	v_mfma_f32_16x16x32_bf16 v[84:87], v[98:101], v[112:115], v[84:87]
	v_mfma_f32_16x16x32_bf16 v[52:55], v[76:79], v[192:195], v[52:55]
	v_mfma_f32_16x16x32_bf16 v[48:51], v[98:101], v[192:195], v[48:51]
	v_mfma_f32_16x16x32_bf16 v[28:31], v[76:79], v[200:203], v[28:31]
	v_mfma_f32_16x16x32_bf16 v[24:27], v[98:101], v[200:203], v[24:27]
	s_barrier
	s_setprio 0
	v_add_u32_e32 v96, 0x10000, v225
	ds_read_b128 v[80:83], v96 offset:2048
	ds_read_b128 v[98:101], v96 offset:3072
	s_add_i32 s29, s46, s18
	v_lshl_add_u64 v[72:73], v[218:219], 0, s[6:7]
	s_mov_b32 m0, s29
	s_nop 0
	global_load_lds_dwordx4 v[72:73], off
	v_lshl_add_u64 v[72:73], v[220:221], 0, s[6:7]
	s_add_i32 m0, s29, 0x2000
	s_nop 0
	global_load_lds_dwordx4 v[72:73], off
	s_waitcnt vmcnt(6)
	s_setprio 1
	s_barrier
	v_mfma_f32_16x16x32_bf16 v[56:59], v[232:235], v[102:105], v[56:59]
	v_mfma_f32_16x16x32_bf16 v[76:79], v[236:239], v[112:115], v[56:59]
	v_mfma_f32_16x16x32_bf16 v[56:59], v[240:243], v[102:105], v[68:71]
	s_add_u32 s44, s44, 0x100
	v_mfma_f32_16x16x32_bf16 v[44:47], v[232:235], v[124:127], v[44:47]
	s_addc_u32 s45, s45, 0
	v_mfma_f32_16x16x32_bf16 v[40:43], v[240:243], v[124:127], v[40:43]
	s_add_u32 s87, s87, 0x100
	v_mfma_f32_16x16x32_bf16 v[20:23], v[232:235], v[196:199], v[20:23]
	s_addc_u32 vcc_lo, vcc_lo, 0
	v_mfma_f32_16x16x32_bf16 v[16:19], v[240:243], v[196:199], v[16:19]
	s_cmp_ge_u32 vcc_hi, s37
	v_mfma_f32_16x16x32_bf16 v[72:75], v[244:247], v[112:115], v[56:59]
	s_mov_b32 s46, vcc_hi
	v_mfma_f32_16x16x32_bf16 v[44:47], v[236:239], v[192:195], v[44:47]
	v_mfma_f32_16x16x32_bf16 v[40:43], v[244:247], v[192:195], v[40:43]
	v_mfma_f32_16x16x32_bf16 v[20:23], v[236:239], v[200:203], v[20:23]
	v_mfma_f32_16x16x32_bf16 v[16:19], v[244:247], v[200:203], v[16:19]
	s_barrier
	s_setprio 0
	s_cbranch_scc0 .LBB0_1021
	s_waitcnt lgkmcnt(0)
	s_mul_i32 s44, s86, 0xc0
	s_add_i32 s44, s44, s19
	s_cmpk_lt_u32 s44, 0x2000
	v_or_b32_e32 v198, s44, v223
	s_cselect_b32 s44, 1, 2
	v_mov_b32_e32 v56, s44
	v_cmp_lt_i32_e32 vcc, s23, v198
	v_lshl_or_b32 v192, s72, 8, v226
	v_ashrrev_i32_e32 v193, 31, v192
	v_cndmask_b32_e32 v228, 0, v56, vcc
	v_mul_u32_u24_e32 v56, 0x1800, v228
	v_lshlrev_b32_e32 v96, 2, v56
	v_lshl_add_u64 v[56:57], s[70:71], 0, v[96:97]
	v_lshlrev_b64 v[68:69], 2, v[192:193]
	v_lshl_add_u64 v[124:125], v[56:57], 0, v[68:69]
	global_load_dwordx4 v[56:59], v[124:125], off
	s_andn2_b64 vcc, exec, s[76:77]
	s_cbranch_vccnz .Lrs_warm_skip
	v_lshl_add_u64 v[202:203], s[66:67], 0, v[96:97]
	v_lshl_add_u64 v[202:203], v[202:203], 0, v[68:69]
	v_lshl_add_u64 v[194:195], s[58:59], 0, v[68:69]
	global_load_dwordx4 v[112:115], v[202:203], off
	global_load_dwordx4 v[104:107], v[194:195], off
	global_load_dwordx4 v[98:101], v[202:203], off offset:16
	global_load_dwordx4 v[230:233], v[194:195], off offset:16
	global_load_dwordx2 v[200:201], v[124:125], off offset:512
	global_load_dwordx2 v[200:201], v[202:203], off offset:512
	global_load_dwordx2 v[200:201], v[194:195], off offset:512
.Lrs_warm_skip:
	v_cndmask_b32_e64 v70, 0, 1, s[78:79]
	v_cmp_ne_u32_e64 s[46:47], 1, v70
	s_andn2_b64 vcc, exec, s[78:79]
	v_lshl_add_u64 v[196:197], s[54:55], 0, v[68:69]
	s_cbranch_vccnz .LBB0_1024
	global_load_dwordx4 v[80:83], v[196:197], off
	global_load_dwordx2 v[200:201], v[196:197], off offset:512
	s_waitcnt vmcnt(0)
	v_pk_mul_f32 v[58:59], v[58:59], v[82:83]
	v_pk_mul_f32 v[56:57], v[56:57], v[80:81]
.LBB0_1024:
	v_lshl_add_u64 v[70:71], s[66:67], 0, v[96:97]
	v_lshl_add_u64 v[202:203], v[70:71], 0, v[68:69]
	v_cndmask_b32_e64 v70, 0, 1, s[76:77]
	v_cmp_ne_u32_e64 s[44:45], 1, v70
	s_andn2_b64 vcc, exec, s[76:77]
	v_lshl_add_u64 v[194:195], s[58:59], 0, v[68:69]
	s_cbranch_vccnz .LBB0_1026
	s_waitcnt vmcnt(0)
	v_pk_add_f32 v[70:71], v[114:115], 1.0 op_sel_hi:[1,0]
	v_pk_add_f32 v[68:69], v[112:113], 1.0 op_sel_hi:[1,0]
	v_pk_mul_f32 v[70:71], v[106:107], v[70:71]
	v_pk_mul_f32 v[68:69], v[104:105], v[68:69]
	global_load_dwordx4 v[80:83], v[124:125], off offset:16
	s_and_b64 vcc, exec, s[46:47]
	s_cbranch_vccz .LBB0_1027
	s_branch .LBB0_1028

.LBB0_1027:
	global_load_dwordx4 v[112:115], v[196:197], off offset:16
	s_waitcnt vmcnt(0)
	v_pk_mul_f32 v[82:83], v[82:83], v[114:115]
	v_pk_mul_f32 v[80:81], v[80:81], v[112:113]
.LBB0_1028:
	s_and_b64 vcc, exec, s[44:45]
	s_cbranch_vccnz .LBB0_1030
	s_waitcnt vmcnt(0)
	v_pk_add_f32 v[100:101], v[100:101], 1.0 op_sel_hi:[1,0]
	v_pk_add_f32 v[98:99], v[98:99], 1.0 op_sel_hi:[1,0]
	v_pk_mul_f32 v[102:103], v[232:233], v[100:101]
	v_pk_mul_f32 v[100:101], v[230:231], v[98:99]
	global_load_dwordx4 v[104:107], v[124:125], off offset:512
	s_and_b64 vcc, exec, s[46:47]
	s_cbranch_vccz .LBB0_1031
	s_branch .LBB0_1032
